# stick-breaking attention: exact workgroup-uniform early exit once every query's accumulated log2(1-beta) sum >= 160 (remaining keys contribute exactly 0.0f); bit-identical outputs
# speedup vs baseline: 1.1943x; 1.1943x over previous
; #define GAS __attribute__((address_space(1)))
; #define ATT_DMAPAIR(p_) do { _Pragma("unroll") for (int s_ = 0; s_ < 2; ++s_) { int tk_, sv_, dv_; tile_desc<MODE>(ATT_IDX(2 * (p_) + s_), u0, r4, tk_, sv_, dv_); \
;             if (tk_ >= 0) ATT_DMA(tk_, sv_, 2 * ((p_) & 1) + s_); } } while (0)
; template <int DK, int MODE>
; __device__ __forceinline__ void attn_unit(LAS unsigned char* lds, const bf16_t* Q, int ldq, const bf16_t* Kp, int ldk, const bf16_t* Vp, int ldv, bf16_t* O, int ldo, int u0, int r4) {
;     ...
;     int tid = threadIdx.x; asm volatile("" : "+v"(tid));
;     const GAS bf16_t* Qg = (const GAS bf16_t*)Q; GAS bf16_t* Og = (GAS bf16_t*)O;
;     const int wave = __builtin_amdgcn_readfirstlane(tid >> 6), lane = tid & 63, r = lane & 31, h = lane >> 5;
;     int tq, tqmin, tqmax;
;     if (MODE == 0) { tqmin = r4 + 4 * (u0 + 32 * wave); tq = tqmin + 4 * r; tqmax = tqmin + 124; }
;     else { tqmin = 256 * u0 + 32 * wave; tq = tqmin + r; tqmax = tqmin + 31; }
;     bf16x8 qf[DK / 16];
; #pragma unroll
;     for (int ks = 0; ks < DK / 16; ++ks) qf[ks] = *(const GAS bf16x8*)(Qg + (size_t)tq * ldq + 16 * ks + 8 * h);
;     f32x16 o[4];
; #pragma unroll
;     for (int b = 0; b < 4; ++b)
; #pragma unroll
;         for (int e = 0; e < 16; ++e) o[b][e] = 0.f;
;     float mrun = -1e30f, lrun = 0.f, Rrun = 0.f;
;     const int ntiles = (MODE == 0) ? 36 : 4 * (u0 + 1);
;     const int drow = lane >> 4, dpos = lane & 15;
;     const int kchunk0 = dpos ^ ((8 * wave + drow) & 15), vchunk = dpos ^ (4 * (drow & 3));
;     ...
;     const unsigned kvo0 = (unsigned)((8 * wave + drow) * ldk * 2), vvo0 = (unsigned)((8 * wave + drow) * ldv * 2);
;     const unsigned kc0b = (unsigned)(kchunk0 * 16), vcb = (unsigned)(vchunk * 16);
;     ...
;     const int npairs = ntiles >> 1;
;     ...
;     __syncthreads();
;     ATT_DMAPAIR(0);
;     asm volatile("s_waitcnt vmcnt(0)" ::: "memory");
;     __builtin_amdgcn_s_barrier(); asm volatile("" ::: "memory");
.LBB0_91:
	s_xor_b64 s[12:13], s[4:5], -1
	s_and_b64 s[4:5], s[4:5], exec
	v_mov_b32_e32 v4, v204
	s_cselect_b32 s4, s22, s21
	v_readfirstlane_b32 s5, v4
	s_ashr_i32 s5, s5, 6
	s_lshl_b32 s39, s4, 8
	s_lshl_b32 s14, s5, 5
	v_and_b32_e32 v165, 31, v4
	s_add_i32 s52, s14, s39
	v_or_b32_e32 v130, s52, v165
	v_ashrrev_i32_e32 v131, 31, v130
	v_bfe_u32 v5, v4, 5, 1
	s_waitcnt lgkmcnt(0)
	v_lshlrev_b64 v[2:3], 12, v[130:131]
	v_lshl_add_u64 v[2:3], s[8:9], 0, v[2:3]
	v_lshlrev_b32_e32 v0, 4, v5
	v_lshl_add_u64 v[2:3], v[2:3], 0, v[0:1]
	v_bfe_u32 v0, v4, 4, 2
	global_load_dwordx4 v[98:101], v[2:3], off
	global_load_dwordx4 v[102:105], v[2:3], off offset:32
	global_load_dwordx4 v[106:109], v[2:3], off offset:64
	global_load_dwordx4 v[110:113], v[2:3], off offset:96
	global_load_dwordx4 v[114:117], v[2:3], off offset:128
	global_load_dwordx4 v[118:121], v[2:3], off offset:160
	global_load_dwordx4 v[122:125], v[2:3], off offset:192
	global_load_dwordx4 v[126:129], v[2:3], off offset:224
	v_and_b32_e32 v6, 15, v4
	v_lshl_or_b32 v2, s5, 3, v0
	s_lshl_b32 s5, s5, 11
	s_lshl_b32 s6, s4, 20
	s_lshl_b32 s53, s4, 2
	v_bitop3_b32 v3, v2, v6, 11 bitop3:0x6c
	s_add_i32 s54, s5, 0
	s_or_b32 s4, s6, 0xc0000
	v_lshlrev_b32_e32 v2, 12, v2
	v_lshlrev_b32_e32 v3, 4, v3
	s_movk_i32 s5, 0x4040
	s_add_u32 s4, s23, s4
	v_lshlrev_b32_e32 v7, 6, v0
	v_lshlrev_b32_e32 v8, 4, v6
	v_or_b32_e32 v0, v3, v2
	v_bitop3_b32 v132, v3, s5, v2 bitop3:0x36
	s_addc_u32 s5, s24, 0
	v_bitop3_b32 v134, v2, v7, v8 bitop3:0xf6
	v_lshl_add_u64 v[2:3], s[4:5], 0, v[0:1]
	v_mov_b32_e32 v133, v1
	v_lshl_add_u64 v[2:3], v[2:3], 0, s[70:71]
	s_mov_b32 m0, s54
	s_barrier
	global_load_lds_dwordx4 v[2:3], off
	v_lshl_add_u64 v[2:3], s[4:5], 0, v[132:133]
	v_mov_b32_e32 v135, v1
	v_lshl_add_u64 v[2:3], v[2:3], 0, s[70:71]
	s_add_i32 m0, s54, 0x400
	v_or_b32_e32 v136, 0x4000, v134
	global_load_lds_dwordx4 v[2:3], off
	v_lshl_add_u64 v[2:3], s[4:5], 0, v[134:135]
	v_mov_b32_e32 v137, v1
	v_lshl_add_u64 v[2:3], v[2:3], 0, s[72:73]
	s_add_i32 m0, s54, 0x4000
	s_bitset1_b32 s6, 19
	global_load_lds_dwordx4 v[2:3], off
	v_lshl_add_u64 v[2:3], s[4:5], 0, v[136:137]
	v_lshl_add_u64 v[2:3], v[2:3], 0, s[72:73]
	s_add_i32 m0, s54, 0x4400
	v_lshrrev_b32_e32 v7, 3, v4
	global_load_lds_dwordx4 v[2:3], off
	s_add_i32 m0, s54, 0x8000
	s_add_u32 s4, s25, s6
	s_addc_u32 s5, s28, 0
	s_add_u32 s6, s29, s6
	s_addc_u32 s7, s38, 0
	global_load_lds_dwordx4 v0, s[4:5]
	s_add_i32 m0, s54, 0x8400
	v_bitop3_b32 v3, v5, v4, 15 bitop3:0x78
	global_load_lds_dwordx4 v132, s[4:5]
	s_add_i32 m0, s54, 0xc000
	v_and_b32_e32 v2, 63, v4
	global_load_lds_dwordx4 v134, s[6:7]
	s_add_i32 m0, s54, 0xc400
	v_lshlrev_b32_e32 v171, 4, v3
	global_load_lds_dwordx4 v136, s[6:7]
	v_bitop3_b32 v3, v5, v6, 2 bitop3:0x36
	v_bfe_u32 v8, v4, 1, 1
	v_lshlrev_b32_e32 v173, 4, v3
	v_cmp_gt_u32_e64 s[6:7], 32, v2
	v_bfe_u32 v2, v4, 2, 2
	v_lshlrev_b32_e32 v3, 10, v5
	v_and_or_b32 v7, v7, 2, v8
	v_lshl_or_b32 v3, v2, 8, v3
	v_lshlrev_b32_e32 v2, 6, v2
	v_lshlrev_b32_e32 v7, 4, v7
	v_or3_b32 v2, v3, v2, v7
	v_lshlrev_b32_e32 v3, 3, v4
	v_and_b32_e32 v3, 8, v3
	v_or_b32_e32 v174, v2, v3
	v_bitop3_b32 v175, v2, 64, v3 bitop3:0x36
	v_bitop3_b32 v176, v2, s26, v3 bitop3:0x36
	v_bitop3_b32 v177, v2, s27, v3 bitop3:0x36
	v_bitop3_b32 v2, v5, v6, 4 bitop3:0x36
	v_lshlrev_b32_e32 v178, 4, v2
	v_bitop3_b32 v2, v5, v6, 6 bitop3:0x36
	v_lshlrev_b32_e32 v179, 4, v2
	v_bitop3_b32 v2, v5, v6, 8 bitop3:0x36
	v_lshlrev_b32_e32 v180, 4, v2
	v_bitop3_b32 v2, v5, v6, 10 bitop3:0x36
	v_lshlrev_b32_e32 v181, 4, v2
	v_bitop3_b32 v2, v5, v6, 12 bitop3:0x36
	v_lshlrev_b32_e32 v172, 2, v5
	v_lshlrev_b32_e32 v182, 4, v2
	v_bitop3_b32 v2, v5, v6, 14 bitop3:0x36
	s_lshr_b32 s4, s54, 9
	s_add_i32 s4, s4, 139360
	v_mov_b32_e32 v245, 0
	v_mov_b32_e32 v244, s4
	ds_write_b32 v244, v245
	s_waitcnt lgkmcnt(0)
	s_waitcnt vmcnt(0)
	s_barrier
	v_lshlrev_b32_e32 v183, 4, v2
	v_sub_u32_e32 v2, v172, v165
	v_mov_b32_e32 v50, v1
	v_mov_b32_e32 v51, v1
	s_add_i32 s4, s53, 4
	v_subrev_u32_e32 v184, s14, v2
	v_mad_i32_i24 v186, v5, -4, s14
	v_mov_b32_e32 v52, v1
	v_mov_b32_e32 v53, v1
	v_mov_b32_e32 v54, v1
	v_mov_b32_e32 v55, v1
	v_mov_b32_e32 v56, v1
	v_mov_b32_e32 v57, v1
	v_mov_b32_e32 v58, v1
	v_mov_b32_e32 v59, v1
	v_mov_b32_e32 v60, v1
	v_mov_b32_e32 v61, v1
	v_mov_b32_e32 v62, v1
	v_mov_b32_e32 v63, v1
	v_mov_b32_e32 v64, v1
	v_mov_b32_e32 v65, v1
	v_mov_b64_e32 v[34:35], v[50:51]
	v_mov_b64_e32 v[18:19], v[50:51]
	v_mov_b64_e32 v[2:3], v[50:51]
	s_or_b32 s55, s52, 31
	s_mov_b32 s56, 1
	s_lshr_b32 s57, s4, 1
	v_lshlrev_b32_e32 v170, 8, v165
	v_sub_u32_e32 v185, s14, v172
	s_mov_b32 s58, 0
	v_mov_b32_e32 v139, 0
	s_mov_b32 s59, 0
	v_mov_b64_e32 v[36:37], v[52:53]
	v_mov_b64_e32 v[38:39], v[54:55]
	v_mov_b64_e32 v[40:41], v[56:57]
	v_mov_b64_e32 v[42:43], v[58:59]
	v_mov_b64_e32 v[44:45], v[60:61]
	v_mov_b64_e32 v[46:47], v[62:63]
	v_mov_b64_e32 v[48:49], v[64:65]
	v_mov_b64_e32 v[20:21], v[52:53]
	v_mov_b64_e32 v[22:23], v[54:55]
	v_mov_b64_e32 v[24:25], v[56:57]
	v_mov_b64_e32 v[26:27], v[58:59]
	v_mov_b64_e32 v[28:29], v[60:61]
	v_mov_b64_e32 v[30:31], v[62:63]
	v_mov_b64_e32 v[32:33], v[64:65]
	v_mov_b64_e32 v[4:5], v[52:53]
	v_mov_b64_e32 v[6:7], v[54:55]
	v_mov_b64_e32 v[8:9], v[56:57]
	v_mov_b64_e32 v[10:11], v[58:59]
	v_mov_b64_e32 v[12:13], v[60:61]
	v_mov_b64_e32 v[14:15], v[62:63]
	v_mov_b64_e32 v[16:17], v[64:65]
	s_waitcnt vmcnt(0)
	s_branch .LBB0_94

; #define LAS __attribute__((address_space(3)))
; #define ATT_DMAPAIR(p_) do { _Pragma("unroll") for (int s_ = 0; s_ < 2; ++s_) { int tk_, sv_, dv_; tile_desc<MODE>(ATT_IDX(2 * (p_) + s_), u0, r4, tk_, sv_, dv_); \
;             if (tk_ >= 0) ATT_DMA(tk_, sv_, 2 * ((p_) & 1) + s_); } } while (0)
; template <int DK, int MODE>
; __device__ __forceinline__ void attn_unit(LAS unsigned char* lds, const bf16_t* Q, int ldq, const bf16_t* Kp, int ldk, const bf16_t* Vp, int ldv, bf16_t* O, int ldo, int u0, int r4) {
;     ...
;     for (int p = 0; p < npairs; ++p) {
;         if (p + 1 < npairs) ATT_DMAPAIR(p + 1);
; #pragma unroll
;         for (int s_ = 0; s_ < 2; ++s_) { int tok0, st, dil; tile_desc<MODE>(ATT_IDX(2 * p + s_), u0, r4, tok0, st, dil);
;             const LAS unsigned char* kb = lds + (2 * (p & 1) + s_) * BUF;
;             if (tok0 >= 0 && ATT_REL(tok0, st, dil)) { f32x16 s[2]; ATT_QK2(s[0], s[1], kb); att_smpv<MODE>(s, o, mrun, lrun, Rrun, tq, tqmin, tok0, st, dil, h, lane, kb + KBYTES); } }
;         asm volatile("s_waitcnt vmcnt(0)" ::: "memory");
;         __builtin_amdgcn_s_barrier(); asm volatile("" ::: "memory");
.LBB0_93:
	v_cmp_gt_f32_e32 vcc, 0x43200000, v139
	s_cmp_eq_u64 vcc, 0
	s_cselect_b32 s4, 1, 0
	s_and_b32 s5, s58, 2
	s_lshl_b32 s5, s5, 4
	s_lshr_b32 s18, s54, 9
	s_add_i32 s5, s5, s18
	s_add_i32 s5, s5, 139328
	v_mov_b32_e32 v245, s4
	v_mov_b32_e32 v244, s5
	ds_write_b32 v244, v245
	s_waitcnt lgkmcnt(0)
	s_waitcnt vmcnt(0)
	s_barrier
	s_add_i32 s53, s53, -2
	s_addk_i32 s59, 0xff80
	v_add_u32_e32 v185, 0x80, v185
	v_add_u32_e32 v186, 0x80, v186
	s_add_i32 s58, s58, 2
	s_andn2_b64 vcc, exec, s[14:15]
	s_add_i32 s56, s56, 1
	s_cbranch_vccz .LBB0_90
.LBB0_94:
	s_cmp_ge_u32 s56, s57
	s_cselect_b64 s[14:15], -1, 0
	s_add_i32 s4, s58, 2
	s_and_b32 s4, s4, 2
	s_lshl_b32 s4, s4, 4
	s_add_i32 s4, s4, 139328
	v_mov_b32_e32 v244, s4
	ds_read_b128 v[246:249], v244
	ds_read_b128 v[250:253], v244 offset:16
	s_waitcnt lgkmcnt(0)
	v_and_b32_e32 v246, v246, v247
	v_and_b32_e32 v248, v248, v249
	v_and_b32_e32 v250, v250, v251
	v_and_b32_e32 v252, v252, v253
	v_and_b32_e32 v246, v246, v248
	v_and_b32_e32 v250, v250, v252
	v_and_b32_e32 v246, v246, v250
	s_nop 0
	v_readfirstlane_b32 s4, v246
	s_cmp_lg_u32 s4, 0
	s_cselect_b64 s[4:5], -1, 0
	s_or_b64 s[14:15], s[14:15], s[4:5]
	s_and_b64 vcc, exec, s[14:15]
	s_cbranch_vccnz .LBB0_99
	s_add_i32 s4, s58, 2
	s_and_b32 s4, s4, 2
	s_add_i32 s5, s53, 1
	s_cmp_lt_i32 s5, 0
	s_cbranch_scc1 .LBB0_97
	s_add_i32 s5, s39, s59
	s_add_i32 s66, s5, 64
	s_lshl_b32 s5, s4, 15
	s_add_i32 s5, s54, s5
	s_lshl_b64 s[18:19], s[66:67], 12
	s_add_u32 s18, s23, s18
	s_addc_u32 s19, s24, s19
	v_lshl_add_u64 v[66:67], s[18:19], 0, v[0:1]
	v_lshl_add_u64 v[66:67], v[66:67], 0, s[70:71]
	s_mov_b32 m0, s5
	s_nop 0
	global_load_lds_dwordx4 v[66:67], off
	v_lshl_add_u64 v[66:67], s[18:19], 0, v[132:133]
	v_lshl_add_u64 v[66:67], v[66:67], 0, s[70:71]
	s_add_i32 m0, s5, 0x400
	s_nop 0
	global_load_lds_dwordx4 v[66:67], off
	v_lshl_add_u64 v[66:67], s[18:19], 0, v[134:135]
	v_lshl_add_u64 v[66:67], v[66:67], 0, s[72:73]
	s_add_i32 m0, s5, 0x4000
	s_nop 0
	global_load_lds_dwordx4 v[66:67], off
	v_lshl_add_u64 v[66:67], s[18:19], 0, v[136:137]
	v_lshl_add_u64 v[66:67], v[66:67], 0, s[72:73]
	s_add_i32 m0, s5, 0x4400
	s_nop 0
	global_load_lds_dwordx4 v[66:67], off

; template <int MODE>
; __device__ __forceinline__ void att_smpv(f32x16 (&s)[2], f32x16 (&o)[4], float& mrun, float& lrun, float& Rrun, int tq, int tqmin, int tok0, int st, int dil, int h, int lane, const LAS unsigned char* vb) {
;     ...
;             if (need_mask) {
; #pragma unroll
;                 for (int e = 0; e < 16; ++e) { const int d = d0 - st * (32 * kk + 8 * (e >> 2) + (e & 3)); s[kk][e] = d > 0 ? s[kk][e] : -INFINITY; }
;             }
.LBB0_99:
	s_add_i32 s36, s39, s59
	s_and_b32 s37, s58, 2
	s_add_i32 s4, s53, 3
	s_add_i32 s18, s36, 0xc0
	s_cmp_lt_i32 s4, 0
	s_cselect_b64 s[4:5], -1, 0
	s_cmp_gt_i32 s18, s55
	s_cselect_b64 s[18:19], -1, 0
	s_or_b64 s[4:5], s[4:5], s[18:19]
	s_and_b64 vcc, exec, s[4:5]
	s_cbranch_vccnz .LBB0_111
	v_cmp_gt_f32_e32 vcc, 0x43200000, v139
	s_cbranch_vccz .LBB0_111
	s_lshl_b32 s4, s37, 15
	s_add_i32 s60, s4, 0
	v_add_u32_e32 v138, s60, v170
	v_add_u32_e32 v70, v138, v171
	ds_read_b128 v[66:69], v70
	ds_read_b128 v[82:85], v70 offset:8192
	v_add_u32_e32 v70, v138, v173
	ds_read_b128 v[140:143], v70
	ds_read_b128 v[144:147], v70 offset:8192
	s_waitcnt lgkmcnt(0)
	v_mfma_f32_32x32x16_bf16 v[66:81], v[66:69], v[98:101], 0
	v_mfma_f32_32x32x16_bf16 v[82:97], v[82:85], v[98:101], 0
	v_add_u32_e32 v152, v138, v178
	ds_read_b128 v[148:151], v152
	ds_read_b128 v[166:169], v152 offset:8192
	v_mfma_f32_32x32x16_bf16 v[66:81], v[140:143], v[102:105], v[66:81]
	v_mfma_f32_32x32x16_bf16 v[82:97], v[144:147], v[102:105], v[82:97]
	v_add_u32_e32 v144, v138, v179
	ds_read_b128 v[140:143], v144
	ds_read_b128 v[144:147], v144 offset:8192
	s_waitcnt lgkmcnt(0)
	v_mfma_f32_32x32x16_bf16 v[66:81], v[148:151], v[106:109], v[66:81]
	v_mfma_f32_32x32x16_bf16 v[82:97], v[166:169], v[106:109], v[82:97]
	v_add_u32_e32 v152, v138, v180
	ds_read_b128 v[148:151], v152
	ds_read_b128 v[166:169], v152 offset:8192
	v_mfma_f32_32x32x16_bf16 v[66:81], v[140:143], v[110:113], v[66:81]
	v_mfma_f32_32x32x16_bf16 v[82:97], v[144:147], v[110:113], v[82:97]
	v_add_u32_e32 v144, v138, v181
	ds_read_b128 v[140:143], v144
	ds_read_b128 v[144:147], v144 offset:8192
	s_waitcnt lgkmcnt(0)
	v_mfma_f32_32x32x16_bf16 v[66:81], v[148:151], v[114:117], v[66:81]
	v_mfma_f32_32x32x16_bf16 v[82:97], v[166:169], v[114:117], v[82:97]
	v_add_u32_e32 v152, v138, v182
	ds_read_b128 v[148:151], v152
	ds_read_b128 v[166:169], v152 offset:8192
	v_mfma_f32_32x32x16_bf16 v[66:81], v[140:143], v[118:121], v[66:81]
	v_mfma_f32_32x32x16_bf16 v[82:97], v[144:147], v[118:121], v[82:97]
	v_add_u32_e32 v138, v138, v183
	ds_read_b128 v[140:143], v138
	ds_read_b128 v[144:147], v138 offset:8192
	s_waitcnt lgkmcnt(0)
	v_mfma_f32_32x32x16_bf16 v[66:81], v[148:151], v[122:125], v[66:81]
	v_mfma_f32_32x32x16_bf16 v[82:97], v[166:169], v[122:125], v[82:97]
	v_mfma_f32_32x32x16_bf16 v[66:81], v[140:143], v[126:129], v[66:81]
	v_mfma_f32_32x32x16_bf16 v[82:97], v[144:147], v[126:129], v[82:97]
	s_add_i32 s18, s36, 0xff
	s_cmp_ge_i32 s18, s52
	s_cselect_b64 s[4:5], -1, 0
	s_cmp_lt_i32 s18, s52
	s_cbranch_scc1 .LBB0_102
	v_add_u32_e32 v138, v165, v186
	v_add_u32_e32 v140, 0xffffff20, v138
	v_cmp_lt_i32_e32 vcc, 0, v140
	v_add_u32_e32 v140, 0xffffff1f, v138
	s_nop 2
	v_cndmask_b32_e32 v82, v214, v82, vcc
	v_cmp_lt_i32_e32 vcc, 0, v140
	v_add_u32_e32 v140, 0xffffff1e, v138
	s_nop 0
	v_cndmask_b32_e32 v83, v214, v83, vcc
	v_cmp_lt_i32_e32 vcc, 0, v140
	v_add_u32_e32 v140, 0xffffff1d, v138
	s_nop 0
	v_cndmask_b32_e32 v84, v214, v84, vcc
	v_cmp_lt_i32_e32 vcc, 0, v140
	v_add_u32_e32 v140, 0xffffff18, v138
	s_nop 0
	v_cndmask_b32_e32 v85, v214, v85, vcc
	v_cmp_lt_i32_e32 vcc, 0, v140
	v_add_u32_e32 v140, 0xffffff17, v138
	s_nop 0
	v_cndmask_b32_e32 v86, v214, v86, vcc
	v_cmp_lt_i32_e32 vcc, 0, v140
	v_add_u32_e32 v140, 0xffffff16, v138
	s_nop 0
	v_cndmask_b32_e32 v87, v214, v87, vcc
	v_cmp_lt_i32_e32 vcc, 0, v140
	v_add_u32_e32 v140, 0xffffff15, v138
	s_nop 0
	v_cndmask_b32_e32 v88, v214, v88, vcc
	v_cmp_lt_i32_e32 vcc, 0, v140
	v_add_u32_e32 v140, 0xffffff10, v138
	s_nop 0
	v_cndmask_b32_e32 v89, v214, v89, vcc
	v_cmp_lt_i32_e32 vcc, 0, v140
	v_add_u32_e32 v140, 0xffffff0f, v138
	s_nop 0
	v_cndmask_b32_e32 v90, v214, v90, vcc
	v_cmp_lt_i32_e32 vcc, 0, v140
	v_add_u32_e32 v140, 0xffffff0e, v138
	s_nop 0
	v_cndmask_b32_e32 v91, v214, v91, vcc
	v_cmp_lt_i32_e32 vcc, 0, v140
	v_add_u32_e32 v140, 0xffffff0d, v138
	s_nop 0
	v_cndmask_b32_e32 v92, v214, v92, vcc
	v_cmp_lt_i32_e32 vcc, 0, v140
	v_add_u32_e32 v140, 0xffffff08, v138
	s_nop 0
	v_cndmask_b32_e32 v93, v214, v93, vcc
	v_cmp_lt_i32_e32 vcc, 0, v140
	v_add_u32_e32 v140, 0xffffff07, v138
	s_nop 0
	v_cndmask_b32_e32 v94, v214, v94, vcc
	v_cmp_lt_i32_e32 vcc, 0, v140
	v_add_u32_e32 v140, 0xffffff06, v138
	v_add_u32_e32 v138, 0xffffff05, v138
	v_cndmask_b32_e32 v95, v214, v95, vcc
	v_cmp_lt_i32_e32 vcc, 0, v140
	s_nop 1
	v_cndmask_b32_e32 v96, v214, v96, vcc
	v_cmp_lt_i32_e32 vcc, 0, v138
	s_nop 1
	v_cndmask_b32_e32 v97, v214, v97, vcc

; template <int MODE>
; __device__ __forceinline__ void att_smpv(f32x16 (&s)[2], f32x16 (&o)[4], float& mrun, float& lrun, float& Rrun, int tq, int tqmin, int tok0, int st, int dil, int h, int lane, const LAS unsigned char* vb) {
;     ...
;             if (need_mask) {
; #pragma unroll
;                 for (int e = 0; e < 16; ++e) { const int d = d0 - st * (32 * kk + 8 * (e >> 2) + (e & 3)); s[kk][e] = d > 0 ? s[kk][e] : -INFINITY; }
;             }
.LBB0_111:
	s_add_i32 s4, s53, 2
	s_add_i32 s18, s36, 0x80
	s_cmp_lt_i32 s4, 0
	s_cselect_b64 s[4:5], -1, 0
	s_cmp_gt_i32 s18, s55
	s_cselect_b64 s[18:19], -1, 0
	s_or_b64 s[4:5], s[4:5], s[18:19]
	s_and_b64 vcc, exec, s[4:5]
	s_cbranch_vccnz .LBB0_93
	v_cmp_gt_f32_e32 vcc, 0x43200000, v139
	s_cbranch_vccz .LBB0_93
	s_lshl_b32 s4, s37, 15
	s_add_i32 s37, s4, 0
	v_add_u32_e32 v138, s37, v170
	v_add_u32_e32 v70, v138, v171
	ds_read_b128 v[66:69], v70 offset:32768
	ds_read_b128 v[82:85], v70 offset:40960
	v_add_u32_e32 v70, v138, v173
	ds_read_b128 v[140:143], v70 offset:32768
	ds_read_b128 v[144:147], v70 offset:40960
	s_waitcnt lgkmcnt(0)
	v_mfma_f32_32x32x16_bf16 v[66:81], v[66:69], v[98:101], 0
	v_mfma_f32_32x32x16_bf16 v[82:97], v[82:85], v[98:101], 0
	v_add_u32_e32 v152, v138, v178
	ds_read_b128 v[148:151], v152 offset:32768
	ds_read_b128 v[166:169], v152 offset:40960
	v_mfma_f32_32x32x16_bf16 v[66:81], v[140:143], v[102:105], v[66:81]
	v_mfma_f32_32x32x16_bf16 v[82:97], v[144:147], v[102:105], v[82:97]
	v_add_u32_e32 v144, v138, v179
	ds_read_b128 v[140:143], v144 offset:32768
	ds_read_b128 v[144:147], v144 offset:40960
	s_waitcnt lgkmcnt(0)
	v_mfma_f32_32x32x16_bf16 v[66:81], v[148:151], v[106:109], v[66:81]
	v_mfma_f32_32x32x16_bf16 v[82:97], v[166:169], v[106:109], v[82:97]
	v_add_u32_e32 v152, v138, v180
	ds_read_b128 v[148:151], v152 offset:32768
	ds_read_b128 v[166:169], v152 offset:40960
	v_mfma_f32_32x32x16_bf16 v[66:81], v[140:143], v[110:113], v[66:81]
	v_mfma_f32_32x32x16_bf16 v[82:97], v[144:147], v[110:113], v[82:97]
	v_add_u32_e32 v144, v138, v181
	ds_read_b128 v[140:143], v144 offset:32768
	ds_read_b128 v[144:147], v144 offset:40960
	s_waitcnt lgkmcnt(0)
	v_mfma_f32_32x32x16_bf16 v[66:81], v[148:151], v[114:117], v[66:81]
	v_mfma_f32_32x32x16_bf16 v[82:97], v[166:169], v[114:117], v[82:97]
	v_add_u32_e32 v152, v138, v182
	ds_read_b128 v[148:151], v152 offset:32768
	ds_read_b128 v[166:169], v152 offset:40960
	v_mfma_f32_32x32x16_bf16 v[66:81], v[140:143], v[118:121], v[66:81]
	v_mfma_f32_32x32x16_bf16 v[82:97], v[144:147], v[118:121], v[82:97]
	v_add_u32_e32 v138, v138, v183
	ds_read_b128 v[140:143], v138 offset:32768
	ds_read_b128 v[144:147], v138 offset:40960
	s_waitcnt lgkmcnt(0)
	v_mfma_f32_32x32x16_bf16 v[66:81], v[148:151], v[122:125], v[66:81]
	v_mfma_f32_32x32x16_bf16 v[82:97], v[166:169], v[122:125], v[82:97]
	v_mfma_f32_32x32x16_bf16 v[66:81], v[140:143], v[126:129], v[66:81]
	v_mfma_f32_32x32x16_bf16 v[82:97], v[144:147], v[126:129], v[82:97]
	s_addk_i32 s36, 0xbf
	s_cmp_ge_i32 s36, s52
	s_cselect_b64 s[4:5], -1, 0
	s_cmp_lt_i32 s36, s52
	s_cbranch_scc1 .LBB0_114
	v_add_u32_e32 v138, v165, v186
	v_add_u32_e32 v140, 0xffffff60, v138
	v_cmp_lt_i32_e32 vcc, 0, v140
	v_add_u32_e32 v140, 0xffffff5f, v138
	s_nop 2
	v_cndmask_b32_e32 v82, v214, v82, vcc
	v_cmp_lt_i32_e32 vcc, 0, v140
	v_add_u32_e32 v140, 0xffffff5e, v138
	s_nop 0
	v_cndmask_b32_e32 v83, v214, v83, vcc
	v_cmp_lt_i32_e32 vcc, 0, v140
	v_add_u32_e32 v140, 0xffffff5d, v138
	s_nop 0
	v_cndmask_b32_e32 v84, v214, v84, vcc
	v_cmp_lt_i32_e32 vcc, 0, v140
	v_add_u32_e32 v140, 0xffffff58, v138
	s_nop 0
	v_cndmask_b32_e32 v85, v214, v85, vcc
	v_cmp_lt_i32_e32 vcc, 0, v140
	v_add_u32_e32 v140, 0xffffff57, v138
	s_nop 0
	v_cndmask_b32_e32 v86, v214, v86, vcc
	v_cmp_lt_i32_e32 vcc, 0, v140
	v_add_u32_e32 v140, 0xffffff56, v138
	s_nop 0
	v_cndmask_b32_e32 v87, v214, v87, vcc
	v_cmp_lt_i32_e32 vcc, 0, v140
	v_add_u32_e32 v140, 0xffffff55, v138
	s_nop 0
	v_cndmask_b32_e32 v88, v214, v88, vcc
	v_cmp_lt_i32_e32 vcc, 0, v140
	v_add_u32_e32 v140, 0xffffff50, v138
	s_nop 0
	v_cndmask_b32_e32 v89, v214, v89, vcc
	v_cmp_lt_i32_e32 vcc, 0, v140
	v_add_u32_e32 v140, 0xffffff4f, v138
	s_nop 0
	v_cndmask_b32_e32 v90, v214, v90, vcc
	v_cmp_lt_i32_e32 vcc, 0, v140
	v_add_u32_e32 v140, 0xffffff4e, v138
	s_nop 0
	v_cndmask_b32_e32 v91, v214, v91, vcc
	v_cmp_lt_i32_e32 vcc, 0, v140
	v_add_u32_e32 v140, 0xffffff4d, v138
	s_nop 0
	v_cndmask_b32_e32 v92, v214, v92, vcc
	v_cmp_lt_i32_e32 vcc, 0, v140
	v_add_u32_e32 v140, 0xffffff48, v138
	s_nop 0
	v_cndmask_b32_e32 v93, v214, v93, vcc
	v_cmp_lt_i32_e32 vcc, 0, v140
	v_add_u32_e32 v140, 0xffffff47, v138
	s_nop 0
	v_cndmask_b32_e32 v94, v214, v94, vcc
	v_cmp_lt_i32_e32 vcc, 0, v140
	v_add_u32_e32 v140, 0xffffff46, v138
	v_add_u32_e32 v138, 0xffffff45, v138
	v_cndmask_b32_e32 v95, v214, v95, vcc
	v_cmp_lt_i32_e32 vcc, 0, v140
	s_nop 1
	v_cndmask_b32_e32 v96, v214, v96, vcc
	v_cmp_lt_i32_e32 vcc, 0, v138
	s_nop 1
	v_cndmask_b32_e32 v97, v214, v97, vcc
